# MM + phase-0 item order: adaLN mod items first on WGs 0..95 then transposes (mode-0 table mf)
# speedup vs baseline: 1.0006x; 1.0006x over previous
; __device__ void phase_prep(const Params& p, LAS unsigned char* lds) {
;     ...
;     constexpr int I_TR = 2 * T_L, I_POOL = I_TR + 128, I_FOUR = I_POOL + 256, I_MOD = I_FOUR + 192, I_ALL = I_MOD + 1;
;     for (int prep_rep = 0; prep_rep < ((PROBE >= 301 && PROBE <= 304) ? 2 : 1); ++prep_rep)
;     for (int it = blockIdx.x; it < I_ALL; it += gridDim.x) {
.Lmy_dp_g256:
	v_writelane_b32 v252, s26, 1
	s_movk_i32 s1, 256
	v_writelane_b32 v252, s1, 2
	s_movk_i32 s1, 369
	v_writelane_b32 v252, s1, 3
	s_movk_i32 s1, 2176
	v_writelane_b32 v252, s1, 0
	s_movk_i32 s1, 96
	v_writelane_b32 v252, s1, 5
	s_movk_i32 s1, 2272
	v_writelane_b32 v252, s1, 6
	s_movk_i32 s1, 97
	v_writelane_b32 v252, s1, 7
	s_movk_i32 s1, -97
	v_writelane_b32 v252, s1, 8
	s_movk_i32 s1, 32767
	v_writelane_b32 v252, s1, 9
	s_movk_i32 s1, 0
	v_writelane_b32 v252, s1, 10
	s_branch .LBB0_650
